# P63: second in-projection epilogue instance (layer-1 tiles computed inside layer 0's down-projection phase) also reads the RoPE table from LDS
# speedup vs baseline: 1.0036x; 1.0036x over previous
.LBB0_1336:
	s_andn2_b64 vcc, exec, s[10:11]
	s_cmp_lg_u32 s35, 0
	s_cselect_b64 s[12:13], -1, 0
	s_lshl_b64 s[8:9], s[8:9], 2
	s_add_u32 s8, s66, s8
	s_addc_u32 s9, s67, s9
	s_lshl_b32 s31, s34, 8
	s_add_i32 s31, s31, s0
	v_or_b32_e32 v200, s31, v206
	v_ashrrev_i32_e32 v201, 31, v200
	v_lshlrev_b64 v[4:5], 6, v[200:201]
	v_lshl_add_u64 v[24:25], v[184:185], 0, v[4:5]
	global_load_dwordx4 v[4:7], v[24:25], off
	v_or_b32_e32 v198, 16, v200
	v_ashrrev_i32_e32 v199, 31, v198
	v_lshlrev_b64 v[8:9], 6, v[198:199]
	v_lshl_add_u64 v[8:9], v[184:185], 0, v[8:9]
	global_load_dwordx4 v[8:11], v[8:9], off
	v_or_b32_e32 v196, 32, v200
	v_ashrrev_i32_e32 v197, 31, v196
	v_lshlrev_b64 v[12:13], 6, v[196:197]
	v_lshl_add_u64 v[12:13], v[184:185], 0, v[12:13]
	global_load_dwordx4 v[12:15], v[12:13], off
	v_or_b32_e32 v194, 48, v200
	v_ashrrev_i32_e32 v195, 31, v194
	v_lshlrev_b64 v[16:17], 6, v[194:195]
	v_lshl_add_u64 v[16:17], v[184:185], 0, v[16:17]
	global_load_dwordx4 v[16:19], v[16:17], off
	v_add_u32_e32 v192, 0x80, v200
	v_ashrrev_i32_e32 v193, 31, v192
	v_lshlrev_b64 v[20:21], 6, v[192:193]
	v_lshl_add_u64 v[20:21], v[184:185], 0, v[20:21]
	global_load_dwordx4 v[20:23], v[20:21], off
	v_add_co_u32_e32 v32, vcc, s59, v24
	v_lshl_add_u32 v190, s33, 8, v208
	s_nop 0
	v_addc_co_u32_e32 v33, vcc, 0, v25, vcc
	global_load_dwordx4 v[24:27], v[32:33], off offset:1024
	global_load_dwordx4 v[28:31], v[32:33], off offset:2048
	global_load_dwordx4 v[66:69], v[32:33], off offset:3072
	v_ashrrev_i32_e32 v191, 31, v190
	v_lshl_add_u64 v[2:3], v[190:191], 2, s[8:9]
	s_and_b64 s[10:11], s[6:7], s[12:13]
	s_andn2_b64 vcc, exec, s[10:11]
	s_waitcnt vmcnt(0)
	v_add_f32_e32 v4, v4, v5
	v_add_f32_e32 v5, v6, v7
	v_add_f32_e32 v4, v4, v5
	s_waitcnt lgkmcnt(0)
	v_mov_b32_e32 v5, v4
	s_nop 1
	v_permlane16_swap_b32_e32 v4, v5
	v_add_f32_e32 v197, v4, v5
	v_add_f32_e32 v4, v8, v9
	v_add_f32_e32 v5, v10, v11
	v_add_f32_e32 v4, v4, v5
	v_mov_b32_e32 v202, v197
	s_nop 1
	v_permlane32_swap_b32_e32 v197, v202
	s_waitcnt lgkmcnt(0)
	v_mov_b32_e32 v5, v4
	s_nop 1
	v_permlane16_swap_b32_e32 v4, v5
	v_add_f32_e32 v222, v4, v5
	v_add_f32_e32 v4, v12, v13
	v_add_f32_e32 v5, v14, v15
	v_add_f32_e32 v4, v4, v5
	v_mov_b32_e32 v223, v222
	s_nop 1
	v_permlane32_swap_b32_e32 v222, v223
	s_waitcnt lgkmcnt(0)
	v_mov_b32_e32 v5, v4
	s_nop 1
	v_permlane16_swap_b32_e32 v4, v5
	v_add_f32_e32 v220, v4, v5
	v_add_f32_e32 v4, v16, v17
	v_add_f32_e32 v5, v18, v19
	v_add_f32_e32 v4, v4, v5
	v_mov_b32_e32 v221, v220
	s_nop 1
	v_permlane32_swap_b32_e32 v220, v221
	s_waitcnt lgkmcnt(0)
	v_mov_b32_e32 v5, v4
	s_nop 1
	v_permlane16_swap_b32_e32 v4, v5
	v_add_f32_e32 v218, v4, v5
	v_add_f32_e32 v4, v20, v21
	v_add_f32_e32 v5, v22, v23
	v_add_f32_e32 v4, v4, v5
	v_mov_b32_e32 v219, v218
	s_nop 1
	v_permlane32_swap_b32_e32 v218, v219
	s_waitcnt lgkmcnt(0)
	v_mov_b32_e32 v5, v4
	s_nop 1
	v_permlane16_swap_b32_e32 v4, v5
	v_add_f32_e32 v216, v4, v5
	v_add_f32_e32 v4, v24, v25
	v_add_f32_e32 v5, v26, v27
	v_add_f32_e32 v4, v4, v5
	v_mov_b32_e32 v217, v216
	s_nop 1
	v_permlane32_swap_b32_e32 v216, v217
	s_waitcnt lgkmcnt(0)
	v_mov_b32_e32 v5, v4
	s_nop 1
	v_permlane16_swap_b32_e32 v4, v5
	v_add_f32_e32 v214, v4, v5
	v_add_f32_e32 v4, v28, v29
	v_add_f32_e32 v5, v30, v31
	v_add_f32_e32 v4, v4, v5
	v_mov_b32_e32 v215, v214
	s_nop 1
	v_permlane32_swap_b32_e32 v214, v215
	s_waitcnt lgkmcnt(0)
	v_mov_b32_e32 v5, v4
	s_nop 1
	v_permlane16_swap_b32_e32 v4, v5
	v_add_f32_e32 v199, v4, v5
	v_add_f32_e32 v4, v66, v67
	v_add_f32_e32 v5, v68, v69
	global_load_dwordx4 v[82:85], v[2:3], off offset:16
	global_load_dwordx4 v[86:89], v[2:3], off
	global_load_dwordx4 v[66:69], v[2:3], off offset:528
	global_load_dwordx4 v[70:73], v[2:3], off offset:512
	v_add_f32_e32 v4, v4, v5
	ds_swizzle_b32 v5, v4 offset:swizzle(SWAP,16)
	v_mov_b32_e32 v201, v199
	v_cndmask_b32_e64 v2, 0, 1, s[10:11]
	s_nop 0
	v_permlane32_swap_b32_e32 v199, v201
	s_waitcnt lgkmcnt(0)
	v_add_f32_e32 v193, v4, v5
	v_mov_b32_e32 v195, v193
	s_nop 1
	v_permlane32_swap_b32_e32 v193, v195
	v_cmp_ne_u32_e64 s[14:15], 1, v2
	s_cbranch_vccnz .LBB0_1338
	s_bfe_u32 s8, s31, 0x50006
	v_mov_b32_e32 v2, s8
	v_cndmask_b32_e64 v2, v206, v2, s[2:3]
	v_lshlrev_b32_e32 v3, 2, v209
	v_lshl_or_b32 v2, v2, 7, v3
	v_add_u32_e32 v2, 0x24000, v2
	ds_read_b128 v[14:17], v2 offset:48
	ds_read_b128 v[10:13], v2 offset:32
	ds_read_b128 v[6:9], v2 offset:16
	s_nop 0
	ds_read_b128 v[2:5], v2
.LBB0_1338:
	s_and_b64 vcc, exec, s[14:15]
	v_mov_b32_e32 v18, 0
	s_cbranch_vccnz .LBB0_1340
	s_bfe_u32 s8, s31, 0x50006
	v_mov_b32_e32 v18, s8
	v_cndmask_b32_e64 v18, v210, v18, s[2:3]
	v_lshlrev_b32_e32 v19, 2, v209
	v_lshl_or_b32 v18, v18, 7, v19
	v_add_u32_e32 v18, 0x24000, v18
	ds_read_b128 v[224:227], v18
	ds_read_b128 v[228:231], v18 offset:16
	ds_read_b128 v[232:235], v18 offset:32
	ds_read_b128 v[236:239], v18 offset:48
	s_waitcnt lgkmcnt(4)
	v_mov_b32_e32 v18, v2
	v_mov_b32_e32 v19, v3
	v_mov_b32_e32 v20, v4
	v_mov_b32_e32 v21, v5
	v_mov_b32_e32 v22, v6
	v_mov_b32_e32 v23, v7
	v_mov_b32_e32 v24, v8
	v_mov_b32_e32 v25, v9
	v_mov_b32_e32 v26, v10
	v_mov_b32_e32 v27, v11
	v_mov_b32_e32 v28, v12
	v_mov_b32_e32 v29, v13
	v_mov_b32_e32 v30, v14
	v_mov_b32_e32 v31, v15
	v_mov_b32_e32 v32, v16
	v_mov_b32_e32 v33, v17
	s_waitcnt lgkmcnt(3)
	v_mov_b64_e32 v[2:3], v[224:225]
	s_waitcnt lgkmcnt(2)
	v_mov_b64_e32 v[6:7], v[228:229]
	s_waitcnt lgkmcnt(1)
	v_mov_b64_e32 v[10:11], v[232:233]
	s_waitcnt lgkmcnt(0)
	v_mov_b64_e32 v[14:15], v[236:237]
	v_mov_b64_e32 v[4:5], v[226:227]
	v_mov_b64_e32 v[8:9], v[230:231]
	v_mov_b64_e32 v[12:13], v[234:235]
	v_mov_b64_e32 v[16:17], v[238:239]
	s_branch .LBB0_1341

.LBB0_1349:
	v_cvt_pk_bf16_f32 v166, v166, v167
	v_cvt_pk_bf16_f32 v167, v168, v169
	v_cvt_pk_bf16_f32 v168, v162, v163
	s_nop 0
	v_cvt_pk_bf16_f32 v169, v164, v165
	global_store_dwordx4 v[170:171], v[166:169], off offset:256
	s_and_b64 vcc, exec, s[14:15]
	s_cbranch_vccnz .LBB0_1351
	s_bfe_u32 s33, s31, 0x50006
	v_mov_b32_e32 v18, s33
	v_cndmask_b32_e64 v18, v211, v18, s[2:3]
	v_lshlrev_b32_e32 v19, 2, v209
	v_lshl_or_b32 v18, v18, 7, v19
	v_add_u32_e32 v18, 0x24000, v18
	ds_read_b128 v[162:165], v18
	ds_read_b128 v[224:227], v18 offset:16
	ds_read_b128 v[228:231], v18 offset:32
	ds_read_b128 v[232:235], v18 offset:48
	v_mov_b64_e32 v[32:33], v[16:17]
	v_mov_b32_e32 v166, v2
	v_mov_b32_e32 v169, v3
	v_mov_b32_e32 v167, v4
	v_mov_b32_e32 v171, v5
	v_mov_b32_e32 v168, v6
	v_mov_b32_e32 v173, v7
	v_mov_b32_e32 v170, v8
	v_mov_b32_e32 v175, v9
	v_mov_b32_e32 v172, v10
	v_mov_b32_e32 v177, v11
	v_mov_b32_e32 v174, v12
	v_mov_b32_e32 v202, v13
	v_mov_b32_e32 v176, v14
	v_mov_b32_e32 v203, v15
	v_mov_b32_e32 v200, v16
	v_mov_b32_e32 v204, v17
	v_mov_b64_e32 v[30:31], v[14:15]
	v_mov_b64_e32 v[28:29], v[12:13]
	v_mov_b64_e32 v[26:27], v[10:11]
	v_mov_b64_e32 v[24:25], v[8:9]
	v_mov_b64_e32 v[22:23], v[6:7]
	v_mov_b64_e32 v[20:21], v[4:5]
	v_mov_b64_e32 v[18:19], v[2:3]
	s_waitcnt lgkmcnt(3)
	v_mov_b64_e32 v[2:3], v[162:163]
	s_waitcnt lgkmcnt(2)
	v_mov_b64_e32 v[6:7], v[224:225]
	s_waitcnt lgkmcnt(1)
	v_mov_b64_e32 v[10:11], v[228:229]
	s_waitcnt lgkmcnt(0)
	v_mov_b64_e32 v[14:15], v[232:233]
	v_mov_b64_e32 v[4:5], v[164:165]
	v_mov_b64_e32 v[8:9], v[226:227]
	v_mov_b64_e32 v[12:13], v[230:231]
	v_mov_b64_e32 v[16:17], v[234:235]
	s_branch .LBB0_1352

.LBB0_1360:
	v_cvt_pk_bf16_f32 v150, v150, v151
	v_cvt_pk_bf16_f32 v151, v152, v153
	v_cvt_pk_bf16_f32 v152, v146, v147
	s_nop 0
	v_cvt_pk_bf16_f32 v153, v148, v149
	global_store_dwordx4 v[154:155], v[150:153], off offset:256
	s_and_b64 vcc, exec, s[14:15]
	s_cbranch_vccnz .LBB0_1362
	s_bfe_u32 s31, s31, 0x50006
	v_mov_b32_e32 v18, s31
	v_cndmask_b32_e64 v18, v212, v18, s[2:3]
	v_lshlrev_b32_e32 v19, 2, v209
	v_lshl_or_b32 v18, v18, 7, v19
	v_add_u32_e32 v18, 0x24000, v18
	ds_read_b128 v[146:149], v18
	ds_read_b128 v[150:153], v18 offset:16
	ds_read_b128 v[154:157], v18 offset:32
	ds_read_b128 v[158:161], v18 offset:48
	v_mov_b64_e32 v[32:33], v[16:17]
	v_mov_b32_e32 v166, v2
	v_mov_b32_e32 v169, v3
	v_mov_b32_e32 v167, v4
	v_mov_b32_e32 v171, v5
	v_mov_b32_e32 v168, v6
	v_mov_b32_e32 v173, v7
	v_mov_b32_e32 v170, v8
	v_mov_b32_e32 v175, v9
	v_mov_b32_e32 v172, v10
	v_mov_b32_e32 v177, v11
	v_mov_b32_e32 v174, v12
	v_mov_b32_e32 v202, v13
	v_mov_b32_e32 v176, v14
	v_mov_b32_e32 v203, v15
	v_mov_b32_e32 v200, v16
	v_mov_b32_e32 v204, v17
	v_mov_b64_e32 v[30:31], v[14:15]
	v_mov_b64_e32 v[28:29], v[12:13]
	v_mov_b64_e32 v[26:27], v[10:11]
	v_mov_b64_e32 v[24:25], v[8:9]
	v_mov_b64_e32 v[22:23], v[6:7]
	v_mov_b64_e32 v[20:21], v[4:5]
	v_mov_b64_e32 v[18:19], v[2:3]
	s_waitcnt lgkmcnt(3)
	v_mov_b64_e32 v[2:3], v[146:147]
	s_waitcnt lgkmcnt(2)
	v_mov_b64_e32 v[6:7], v[150:151]
	s_waitcnt lgkmcnt(1)
	v_mov_b64_e32 v[10:11], v[154:155]
	s_waitcnt lgkmcnt(0)
	v_mov_b64_e32 v[14:15], v[158:159]
	v_mov_b64_e32 v[4:5], v[148:149]
	v_mov_b64_e32 v[8:9], v[152:153]
	v_mov_b64_e32 v[12:13], v[156:157]
	v_mov_b64_e32 v[16:17], v[160:161]

.LBB0_1370:
	v_cvt_pk_bf16_f32 v134, v134, v135
	v_cvt_pk_bf16_f32 v135, v136, v137
	v_cvt_pk_bf16_f32 v136, v130, v131
	s_nop 0
	v_cvt_pk_bf16_f32 v137, v132, v133
	global_store_dwordx4 v[138:139], v[134:137], off offset:256
	s_and_b64 vcc, exec, s[14:15]
	s_cbranch_vccnz .LBB0_1372
	v_bfe_u32 v18, v192, 6, 5
	v_cndmask_b32_e64 v18, v206, v18, s[2:3]
	v_lshlrev_b32_e32 v19, 2, v209
	v_lshl_or_b32 v18, v18, 7, v19
	v_add_u32_e32 v18, 0x24000, v18
	ds_read_b128 v[130:133], v18
	ds_read_b128 v[134:137], v18 offset:16
	ds_read_b128 v[138:141], v18 offset:32
	ds_read_b128 v[142:145], v18 offset:48
	v_mov_b64_e32 v[32:33], v[16:17]
	v_mov_b32_e32 v166, v2
	v_mov_b32_e32 v169, v3
	v_mov_b32_e32 v167, v4
	v_mov_b32_e32 v171, v5
	v_mov_b32_e32 v168, v6
	v_mov_b32_e32 v173, v7
	v_mov_b32_e32 v170, v8
	v_mov_b32_e32 v175, v9
	v_mov_b32_e32 v172, v10
	v_mov_b32_e32 v177, v11
	v_mov_b32_e32 v174, v12
	v_mov_b32_e32 v202, v13
	v_mov_b32_e32 v176, v14
	v_mov_b32_e32 v203, v15
	v_mov_b32_e32 v200, v16
	v_mov_b32_e32 v204, v17
	v_mov_b64_e32 v[30:31], v[14:15]
	v_mov_b64_e32 v[28:29], v[12:13]
	v_mov_b64_e32 v[26:27], v[10:11]
	v_mov_b64_e32 v[24:25], v[8:9]
	v_mov_b64_e32 v[22:23], v[6:7]
	v_mov_b64_e32 v[20:21], v[4:5]
	v_mov_b64_e32 v[18:19], v[2:3]
	s_waitcnt lgkmcnt(3)
	v_mov_b64_e32 v[2:3], v[130:131]
	s_waitcnt lgkmcnt(2)
	v_mov_b64_e32 v[6:7], v[134:135]
	s_waitcnt lgkmcnt(1)
	v_mov_b64_e32 v[10:11], v[138:139]
	s_waitcnt lgkmcnt(0)
	v_mov_b64_e32 v[14:15], v[142:143]
	v_mov_b64_e32 v[4:5], v[132:133]
	v_mov_b64_e32 v[8:9], v[136:137]
	v_mov_b64_e32 v[12:13], v[140:141]
	v_mov_b64_e32 v[16:17], v[144:145]

.LBB0_1380:
	v_cvt_pk_bf16_f32 v118, v118, v119
	v_cvt_pk_bf16_f32 v119, v120, v121
	v_cvt_pk_bf16_f32 v120, v114, v115
	s_nop 0
	v_cvt_pk_bf16_f32 v121, v116, v117
	global_store_dwordx4 v[122:123], v[118:121], off offset:256
	s_and_b64 vcc, exec, s[14:15]
	s_cbranch_vccnz .LBB0_1382
	v_bfe_u32 v18, v192, 6, 5
	v_cndmask_b32_e64 v18, v210, v18, s[2:3]
	v_lshlrev_b32_e32 v19, 2, v209
	v_lshl_or_b32 v18, v18, 7, v19
	v_add_u32_e32 v18, 0x24000, v18
	ds_read_b128 v[114:117], v18
	ds_read_b128 v[118:121], v18 offset:16
	ds_read_b128 v[122:125], v18 offset:32
	ds_read_b128 v[126:129], v18 offset:48
	v_mov_b64_e32 v[32:33], v[16:17]
	v_mov_b32_e32 v166, v2
	v_mov_b32_e32 v169, v3
	v_mov_b32_e32 v167, v4
	v_mov_b32_e32 v171, v5
	v_mov_b32_e32 v168, v6
	v_mov_b32_e32 v173, v7
	v_mov_b32_e32 v170, v8
	v_mov_b32_e32 v175, v9
	v_mov_b32_e32 v172, v10
	v_mov_b32_e32 v177, v11
	v_mov_b32_e32 v174, v12
	v_mov_b32_e32 v202, v13
	v_mov_b32_e32 v176, v14
	v_mov_b32_e32 v203, v15
	v_mov_b32_e32 v200, v16
	v_mov_b32_e32 v204, v17
	v_mov_b64_e32 v[30:31], v[14:15]
	v_mov_b64_e32 v[28:29], v[12:13]
	v_mov_b64_e32 v[26:27], v[10:11]
	v_mov_b64_e32 v[24:25], v[8:9]
	v_mov_b64_e32 v[22:23], v[6:7]
	v_mov_b64_e32 v[20:21], v[4:5]
	v_mov_b64_e32 v[18:19], v[2:3]
	s_waitcnt lgkmcnt(3)
	v_mov_b64_e32 v[2:3], v[114:115]
	s_waitcnt lgkmcnt(2)
	v_mov_b64_e32 v[6:7], v[118:119]
	s_waitcnt lgkmcnt(1)
	v_mov_b64_e32 v[10:11], v[122:123]
	s_waitcnt lgkmcnt(0)
	v_mov_b64_e32 v[14:15], v[126:127]
	v_mov_b64_e32 v[4:5], v[116:117]
	v_mov_b64_e32 v[8:9], v[120:121]
	v_mov_b64_e32 v[12:13], v[124:125]
	v_mov_b64_e32 v[16:17], v[128:129]

.LBB0_1390:
	v_cvt_pk_bf16_f32 v102, v102, v103
	v_cvt_pk_bf16_f32 v103, v104, v105
	v_cvt_pk_bf16_f32 v104, v98, v99
	s_nop 0
	v_cvt_pk_bf16_f32 v105, v100, v101
	global_store_dwordx4 v[106:107], v[102:105], off offset:256
	s_and_b64 vcc, exec, s[14:15]
	s_cbranch_vccnz .LBB0_1392
	v_bfe_u32 v18, v192, 6, 5
	v_cndmask_b32_e64 v18, v211, v18, s[2:3]
	v_lshlrev_b32_e32 v19, 2, v209
	v_lshl_or_b32 v18, v18, 7, v19
	v_add_u32_e32 v18, 0x24000, v18
	ds_read_b128 v[98:101], v18
	ds_read_b128 v[102:105], v18 offset:16
	ds_read_b128 v[106:109], v18 offset:32
	ds_read_b128 v[110:113], v18 offset:48
	v_mov_b64_e32 v[32:33], v[16:17]
	v_mov_b32_e32 v166, v2
	v_mov_b32_e32 v169, v3
	v_mov_b32_e32 v167, v4
	v_mov_b32_e32 v171, v5
	v_mov_b32_e32 v168, v6
	v_mov_b32_e32 v173, v7
	v_mov_b32_e32 v170, v8
	v_mov_b32_e32 v175, v9
	v_mov_b32_e32 v172, v10
	v_mov_b32_e32 v177, v11
	v_mov_b32_e32 v174, v12
	v_mov_b32_e32 v202, v13
	v_mov_b32_e32 v176, v14
	v_mov_b32_e32 v203, v15
	v_mov_b32_e32 v200, v16
	v_mov_b32_e32 v204, v17
	v_mov_b64_e32 v[30:31], v[14:15]
	v_mov_b64_e32 v[28:29], v[12:13]
	v_mov_b64_e32 v[26:27], v[10:11]
	v_mov_b64_e32 v[24:25], v[8:9]
	v_mov_b64_e32 v[22:23], v[6:7]
	v_mov_b64_e32 v[20:21], v[4:5]
	v_mov_b64_e32 v[18:19], v[2:3]
	s_waitcnt lgkmcnt(3)
	v_mov_b64_e32 v[2:3], v[98:99]
	s_waitcnt lgkmcnt(2)
	v_mov_b64_e32 v[6:7], v[102:103]
	s_waitcnt lgkmcnt(1)
	v_mov_b64_e32 v[10:11], v[106:107]
	s_waitcnt lgkmcnt(0)
	v_mov_b64_e32 v[14:15], v[110:111]
	v_mov_b64_e32 v[4:5], v[100:101]
	v_mov_b64_e32 v[8:9], v[104:105]
	v_mov_b64_e32 v[12:13], v[108:109]
	v_mov_b64_e32 v[16:17], v[112:113]

.LBB0_1400:
	v_cvt_pk_bf16_f32 v78, v78, v79
	v_cvt_pk_bf16_f32 v79, v80, v81
	v_cvt_pk_bf16_f32 v80, v74, v75
	s_nop 0
	v_cvt_pk_bf16_f32 v81, v76, v77
	global_store_dwordx4 v[90:91], v[78:81], off offset:256
	s_and_b64 vcc, exec, s[14:15]
	s_cbranch_vccnz .LBB0_1402
	v_bfe_u32 v18, v192, 6, 5
	v_cndmask_b32_e64 v18, v212, v18, s[2:3]
	v_lshlrev_b32_e32 v19, 2, v209
	v_lshl_or_b32 v18, v18, 7, v19
	v_add_u32_e32 v18, 0x24000, v18
	ds_read_b128 v[74:77], v18
	ds_read_b128 v[78:81], v18 offset:16
	ds_read_b128 v[90:93], v18 offset:32
	ds_read_b128 v[94:97], v18 offset:48
	v_mov_b64_e32 v[32:33], v[16:17]
	v_mov_b32_e32 v166, v2
	v_mov_b32_e32 v169, v3
	v_mov_b32_e32 v167, v4
	v_mov_b32_e32 v171, v5
	v_mov_b32_e32 v168, v6
	v_mov_b32_e32 v173, v7
	v_mov_b32_e32 v170, v8
	v_mov_b32_e32 v175, v9
	v_mov_b32_e32 v172, v10
	v_mov_b32_e32 v177, v11
	v_mov_b32_e32 v174, v12
	v_mov_b32_e32 v202, v13
	v_mov_b32_e32 v176, v14
	v_mov_b32_e32 v203, v15
	v_mov_b32_e32 v200, v16
	v_mov_b32_e32 v204, v17
	v_mov_b64_e32 v[30:31], v[14:15]
	v_mov_b64_e32 v[28:29], v[12:13]
	v_mov_b64_e32 v[26:27], v[10:11]
	v_mov_b64_e32 v[24:25], v[8:9]
	v_mov_b64_e32 v[22:23], v[6:7]
	v_mov_b64_e32 v[20:21], v[4:5]
	v_mov_b64_e32 v[18:19], v[2:3]
	s_waitcnt lgkmcnt(3)
	v_mov_b64_e32 v[2:3], v[74:75]
	s_waitcnt lgkmcnt(2)
	v_mov_b64_e32 v[6:7], v[78:79]
	s_waitcnt lgkmcnt(1)
	v_mov_b64_e32 v[10:11], v[90:91]
	s_waitcnt lgkmcnt(0)
	v_mov_b64_e32 v[14:15], v[94:95]
	v_mov_b64_e32 v[4:5], v[76:77]
	v_mov_b64_e32 v[8:9], v[80:81]
	v_mov_b64_e32 v[12:13], v[92:93]
	v_mov_b64_e32 v[16:17], v[96:97]
